# s_setprio: flips deleted, static priority raise for waves 0-3 (other half)
# speedup vs baseline: 1.0042x; 1.0022x over previous
_Z6k_mega6Params:
	s_load_dwordx16 s[40:55], s[0:1], 0x240
	s_load_dword s3, s[0:1], 0x288
	s_load_dwordx2 s[38:39], s[0:1], 0x280
	s_add_u32 s8, s0, 0x280
	s_addc_u32 s9, s1, 0
	v_and_b32_e32 v136, 0x3ff, v0
	s_waitcnt lgkmcnt(0)
	v_writelane_b32 v253, s3, 0
	v_readfirstlane_b32 s4, v136
	s_nop 3
	s_lshr_b32 s4, s4, 6
	s_cmp_ge_u32 s4, 4
	s_cbranch_scc1 .Lprio_done
	s_setprio 1
